# attention: tile-max cross-half reduce moved into the rare rescale path (per-lane half max is enough for the wave-uniform threshold test), on top of deferred row-sum reduce
# baseline (speedup 1.0000x reference)
; DI void finishSM(f32x16& p0, f32x16& p1, float alpha, float& l_reg, bf16x8& pa0, bf16x8& pa1, bf16x8& pa2, bf16x8& pa3) {
; #pragma unroll
;     for (int r = 0; r < 16; ++r) p1[r] = __builtin_amdgcn_exp2f(p1[r]);
;     float ps = 0;
; #pragma unroll
;     for (int r = 0; r < 16; ++r) ps += p0[r];
; #pragma unroll
;     for (int r = 0; r < 16; ++r) ps += p1[r];
;     { auto rr = __builtin_amdgcn_permlane32_swap(__float_as_uint(ps), __float_as_uint(ps), false, false);
;       ps = __uint_as_float(rr[0]) + __uint_as_float(rr[1]); }
;     l_reg = l_reg * alpha + ps;
;     ...
;     PK4(p0, 0, pa0); PK4(p0, 8, pa1); PK4(p1, 0, pa2); PK4(p1, 8, pa3);
;     ...
; }
; DI void qkt(f32x16& p0, f32x16& p1, const char* Ks, const bf16x8* qr, const f32x16& negm, int r32, int hi) {
;     { const bf16x8 b0 = *reinterpret_cast<const bf16x8*>(Ks + KSWZ(r32, hi * 16));
;       const bf16x8 b1 = *reinterpret_cast<const bf16x8*>(Ks + KSWZ(32 + r32, hi * 16));
;       p0 = __builtin_amdgcn_mfma_f32_32x32x16_bf16(b0, qr[0], negm, 0, 0, 0);
;       p1 = __builtin_amdgcn_mfma_f32_32x32x16_bf16(b1, qr[0], negm, 0, 0, 0); }
; #pragma unroll
;     for (int d0 = 1; d0 < 4; ++d0) { const int cb = (d0 * 16 + hi * 8) * 2;
;         const bf16x8 b0 = *reinterpret_cast<const bf16x8*>(Ks + KSWZ(r32, cb));
;         const bf16x8 b1 = *reinterpret_cast<const bf16x8*>(Ks + KSWZ(32 + r32, cb));
;         p0 = __builtin_amdgcn_mfma_f32_32x32x16_bf16(b0, qr[d0], p0, 0, 0, 0);
;         p1 = __builtin_amdgcn_mfma_f32_32x32x16_bf16(b1, qr[d0], p1, 0, 0, 0); }
; }
; DI int v_st(int k, int c) { const int kk = (k & ~0xC) | ((k & 4) << 1) | ((k & 8) >> 1); return ((kk >> 3) * 4 + (c >> 5)) * 512 + ((kk & 7) * 32 + (c & 31)) * 2; }
; DI int v_rd_base(int lane) { return ((lane & 3) << 3) | (((lane >> 2) & 3) << 6) | (((lane >> 4) & 1) << 5) | (((lane >> 5) & 1) << 8); }
; template <int OFF> DI s16x4 tr_read(int vb) { s16x4 r; asm volatile("ds_read_b64_tr_b16 %0, %1 offset:%2" : "=&v"(r) : "v"(vb), "i"(OFF) : "memory"); return r; }
; template <int D0> DI void pv_one(f32x16& od, int vb, bf16x8 pa0, bf16x8 pa1, bf16x8 pa2, bf16x8 pa3) {
;     const s16x4 l0 = tr_read<v_rd_off(D0, 0, 0)>(vb), h0 = tr_read<v_rd_off(D0, 0, 1)>(vb), l1 = tr_read<v_rd_off(D0, 1, 0)>(vb), h1 = tr_read<v_rd_off(D0, 1, 1)>(vb);
.LBB0_1038:
	ds_read_b128 v[80:83], v217 offset:40960
	ds_read_b128 v[84:87], v217 offset:45056
	v_exp_f32_e32 v88, v96
	v_exp_f32_e32 v89, v97
	v_exp_f32_e32 v90, v98
	s_waitcnt lgkmcnt(1)
	v_mfma_f32_32x32x16_bf16 v[128:143], v[80:83], v[148:151], v[64:79]
	v_exp_f32_e32 v91, v99
	v_exp_f32_e32 v92, v100
	v_exp_f32_e32 v93, v101
	v_exp_f32_e32 v94, v102
	v_exp_f32_e32 v95, v103
	v_exp_f32_e32 v96, v104
	v_exp_f32_e32 v97, v105
	s_waitcnt lgkmcnt(0)
	v_mfma_f32_32x32x16_bf16 v[112:127], v[84:87], v[148:151], v[64:79]
	ds_read_b128 v[80:83], v218 offset:40960
	ds_read_b128 v[84:87], v218 offset:45056
	v_exp_f32_e32 v98, v106
	v_exp_f32_e32 v99, v107
	v_exp_f32_e32 v100, v108
	v_exp_f32_e32 v101, v109
	v_exp_f32_e32 v102, v110
	v_exp_f32_e32 v103, v111
	s_waitcnt lgkmcnt(1)
	v_mfma_f32_32x32x16_bf16 v[128:143], v[80:83], v[144:147], v[128:143]
	s_waitcnt lgkmcnt(0)
	v_mfma_f32_32x32x16_bf16 v[112:127], v[84:87], v[144:147], v[112:127]
	ds_read_b128 v[80:83], v219 offset:40960
	ds_read_b128 v[84:87], v219 offset:45056
	s_waitcnt lgkmcnt(1)
	v_mfma_f32_32x32x16_bf16 v[128:143], v[80:83], v[152:155], v[128:143]
	s_waitcnt lgkmcnt(0)
	v_mfma_f32_32x32x16_bf16 v[112:127], v[84:87], v[152:155], v[112:127]
	ds_read_b128 v[80:83], v216 offset:40960
	ds_read_b128 v[84:87], v216 offset:45056
	s_waitcnt lgkmcnt(1)
	v_mfma_f32_32x32x16_bf16 v[128:143], v[80:83], v[156:159], v[128:143]
	v_add_f32_e32 v80, v209, v207
	v_add_f32_e32 v80, v183, v80
	v_add_f32_e32 v80, v208, v80
	v_add_f32_e32 v80, v181, v80
	v_add_f32_e32 v80, v206, v80
	v_add_f32_e32 v80, v180, v80
	v_add_f32_e32 v80, v182, v80
	v_add_f32_e32 v80, v173, v80
	v_add_f32_e32 v80, v175, v80
	v_add_f32_e32 v80, v172, v80
	v_add_f32_e32 v80, v174, v80
	v_add_f32_e32 v80, v177, v80
	v_add_f32_e32 v80, v179, v80
	v_add_f32_e32 v80, v176, v80
	v_add_f32_e32 v80, v178, v80
	v_add_f32_e32 v80, v88, v80
	v_add_f32_e32 v80, v89, v80
	v_add_f32_e32 v80, v90, v80
	v_add_f32_e32 v80, v91, v80
	v_add_f32_e32 v80, v92, v80
	v_add_f32_e32 v80, v93, v80
	v_add_f32_e32 v80, v94, v80
	v_add_f32_e32 v80, v95, v80
	v_add_f32_e32 v80, v96, v80
	v_add_f32_e32 v80, v97, v80
	s_waitcnt lgkmcnt(0)
	v_mfma_f32_32x32x16_bf16 v[112:127], v[84:87], v[156:159], v[112:127]
	v_add_f32_e32 v80, v98, v80
	v_add_f32_e32 v80, v99, v80
	v_add_f32_e32 v80, v100, v80
	v_add_f32_e32 v80, v101, v80
	v_add_f32_e32 v80, v102, v80
	v_add_f32_e32 v222, v103, v80
	v_cvt_pk_bf16_f32 v80, v207, v209
	v_cvt_pk_bf16_f32 v81, v183, v208
	v_cvt_pk_bf16_f32 v82, v181, v206
	v_cvt_pk_bf16_f32 v83, v180, v182
	v_cvt_pk_bf16_f32 v84, v173, v175
	v_cvt_pk_bf16_f32 v85, v172, v174
	v_cvt_pk_bf16_f32 v86, v177, v179
	v_cvt_pk_bf16_f32 v87, v176, v178
	v_cvt_pk_bf16_f32 v88, v88, v89
	v_cvt_pk_bf16_f32 v89, v90, v91
	v_cvt_pk_bf16_f32 v90, v92, v93
	v_cvt_pk_bf16_f32 v91, v94, v95
	v_cvt_pk_bf16_f32 v92, v96, v97
	v_cvt_pk_bf16_f32 v93, v98, v99
	v_cvt_pk_bf16_f32 v94, v100, v101
	v_cvt_pk_bf16_f32 v95, v102, v103
	global_load_dwordx4 v[172:175], v203, s[98:99]
	global_load_dwordx4 v[176:179], v204, s[98:99]
	global_load_dwordx4 v[180:183], v202, s[100:101]
	s_add_u32 s98, s98, 0x20000
	s_addc_u32 s99, s99, 0
	s_add_u32 s100, s100, 0x20000
	s_addc_u32 s101, s101, 0
	ds_read_b64_tr_b16 v[96:97], v220 offset:0
	ds_read_b64_tr_b16 v[98:99], v220 offset:0x100
	ds_read_b64_tr_b16 v[100:101], v220 offset:0x1000
	ds_read_b64_tr_b16 v[102:103], v220 offset:0x1100
	ds_read_b64_tr_b16 v[104:105], v220 offset:0x2000
	ds_read_b64_tr_b16 v[106:107], v220 offset:0x2100
	ds_read_b64_tr_b16 v[108:109], v220 offset:0x3000
	ds_read_b64_tr_b16 v[110:111], v220 offset:0x3100
	s_waitcnt lgkmcnt(0)
	s_nop 0
	v_mfma_f32_32x32x16_bf16 v[48:63], v[80:83], v[96:99], v[48:63]
	ds_read_b64_tr_b16 v[96:97], v220 offset:0x200
	ds_read_b64_tr_b16 v[98:99], v220 offset:0x300
	v_mfma_f32_32x32x16_bf16 v[48:63], v[84:87], v[100:103], v[48:63]
	ds_read_b64_tr_b16 v[100:101], v220 offset:0x1200
	ds_read_b64_tr_b16 v[102:103], v220 offset:0x1300
	v_mfma_f32_32x32x16_bf16 v[48:63], v[88:91], v[104:107], v[48:63]
	ds_read_b64_tr_b16 v[104:105], v220 offset:0x2200
	ds_read_b64_tr_b16 v[106:107], v220 offset:0x2300
	v_mfma_f32_32x32x16_bf16 v[48:63], v[92:95], v[108:111], v[48:63]
	ds_read_b64_tr_b16 v[108:109], v220 offset:0x3200
	ds_read_b64_tr_b16 v[110:111], v220 offset:0x3300
	s_waitcnt lgkmcnt(0)
	v_mfma_f32_32x32x16_bf16 v[32:47], v[80:83], v[96:99], v[32:47]
	ds_read_b64_tr_b16 v[96:97], v220 offset:0x400
	ds_read_b64_tr_b16 v[98:99], v220 offset:0x500
	v_mfma_f32_32x32x16_bf16 v[32:47], v[84:87], v[100:103], v[32:47]
	ds_read_b64_tr_b16 v[100:101], v220 offset:0x1400
	ds_read_b64_tr_b16 v[102:103], v220 offset:0x1500
	v_mfma_f32_32x32x16_bf16 v[32:47], v[88:91], v[104:107], v[32:47]
	ds_read_b64_tr_b16 v[104:105], v220 offset:0x2400
	ds_read_b64_tr_b16 v[106:107], v220 offset:0x2500
	v_mfma_f32_32x32x16_bf16 v[32:47], v[92:95], v[108:111], v[32:47]
	ds_read_b64_tr_b16 v[108:109], v220 offset:0x3400
	ds_read_b64_tr_b16 v[110:111], v220 offset:0x3500
	s_waitcnt lgkmcnt(0)
	v_mfma_f32_32x32x16_bf16 v[16:31], v[80:83], v[96:99], v[16:31]
	ds_read_b64_tr_b16 v[96:97], v220 offset:0x600
	ds_read_b64_tr_b16 v[98:99], v220 offset:0x700
	v_mfma_f32_32x32x16_bf16 v[16:31], v[84:87], v[100:103], v[16:31]
	ds_read_b64_tr_b16 v[100:101], v220 offset:0x1600
	ds_read_b64_tr_b16 v[102:103], v220 offset:0x1700
	v_mfma_f32_32x32x16_bf16 v[16:31], v[88:91], v[104:107], v[16:31]
	ds_read_b64_tr_b16 v[104:105], v220 offset:0x2600
	ds_read_b64_tr_b16 v[106:107], v220 offset:0x2700
	v_mfma_f32_32x32x16_bf16 v[16:31], v[92:95], v[108:111], v[16:31]
	ds_read_b64_tr_b16 v[108:109], v220 offset:0x3600
	ds_read_b64_tr_b16 v[110:111], v220 offset:0x3700
	s_waitcnt lgkmcnt(0)
	v_mfma_f32_32x32x16_bf16 v[0:15], v[80:83], v[96:99], v[0:15]
	v_max_f32_e32 v80, v128, v129
	v_max3_f32 v80, v80, v130, v131
	v_max3_f32 v80, v80, v132, v133
	v_max3_f32 v80, v80, v134, v135
	v_max3_f32 v80, v80, v136, v137
	v_mfma_f32_32x32x16_bf16 v[0:15], v[84:87], v[100:103], v[0:15]
	v_max3_f32 v80, v80, v138, v139
	v_max3_f32 v80, v80, v140, v141
	v_max3_f32 v80, v80, v142, v143
	v_max3_f32 v80, v80, v112, v113
	v_max3_f32 v80, v80, v114, v115
	v_max3_f32 v80, v80, v116, v117
	v_max3_f32 v80, v80, v118, v119
	v_mfma_f32_32x32x16_bf16 v[0:15], v[88:91], v[104:107], v[0:15]
	v_max3_f32 v80, v80, v120, v121
	v_max3_f32 v80, v80, v122, v123
	v_max3_f32 v80, v80, v124, v125
	v_max3_f32 v80, v80, v126, v127
	v_mfma_f32_32x32x16_bf16 v[0:15], v[92:95], v[108:111], v[0:15]
	v_cmp_ngt_f32_e32 vcc, s83, v200
	v_cmp_ge_f32_e64 s[8:9], s63, v80
	s_and_b64 s[4:5], vcc, s[8:9]
	s_cmp_eq_u64 s[4:5], exec
	s_cbranch_scc0 .LBB0_1057
	v_mov_b32_e32 v224, 1.0

; #define SBAR() __builtin_amdgcn_sched_barrier(0)
; template <int OFF> DI s16x4 tr_read(int vb) { s16x4 r; asm volatile("ds_read_b64_tr_b16 %0, %1 offset:%2" : "=&v"(r) : "v"(vb), "i"(OFF) : "memory"); return r; }
; DI void partialSM(f32x16& p0, f32x16& p1, float& m_reg, f32x16& negm, float& alpha) {
;     constexpr float THR2 = THR * 1.4426950408889634f;
;     float pmax = p0[0];
; #pragma unroll
;     for (int r = 1; r < 16; ++r) pmax = fmaxf(pmax, p0[r]);
; #pragma unroll
;     for (int r = 0; r < 16; ++r) pmax = fmaxf(pmax, p1[r]);
;     { auto rr = __builtin_amdgcn_permlane32_swap(__float_as_uint(pmax), __float_as_uint(pmax), false, false);
;       pmax = fmaxf(__uint_as_float(rr[0]), __uint_as_float(rr[1])); }
;     const bool first = m_reg < -1e29f;
;     if (__builtin_expect(__all(!first && pmax <= THR2), 1)) { alpha = 1.f; }
; template <int D0> DI void pv_one(f32x16& od, int vb, bf16x8 pa0, bf16x8 pa1, bf16x8 pa2, bf16x8 pa3) {
;     const s16x4 l0 = tr_read<v_rd_off(D0, 0, 0)>(vb), h0 = tr_read<v_rd_off(D0, 0, 1)>(vb), l1 = tr_read<v_rd_off(D0, 1, 0)>(vb), h1 = tr_read<v_rd_off(D0, 1, 1)>(vb);
;     const s16x4 l2 = tr_read<v_rd_off(D0, 2, 0)>(vb), h2 = tr_read<v_rd_off(D0, 2, 1)>(vb), l3 = tr_read<v_rd_off(D0, 3, 0)>(vb), h3 = tr_read<v_rd_off(D0, 3, 1)>(vb);
;     asm volatile("s_waitcnt lgkmcnt(0)" ::: "memory"); SBAR();
;     ...
;     od = __builtin_amdgcn_mfma_f32_32x32x16_bf16(pa0, PKV(l0, h0), od, 0, 0, 0);
;     od = __builtin_amdgcn_mfma_f32_32x32x16_bf16(pa1, PKV(l1, h1), od, 0, 0, 0);
;     od = __builtin_amdgcn_mfma_f32_32x32x16_bf16(pa2, PKV(l2, h2), od, 0, 0, 0);
;     od = __builtin_amdgcn_mfma_f32_32x32x16_bf16(pa3, PKV(l3, h3), od, 0, 0, 0);
;     ...
; }
; DI void pv_d0(f32x16* o, int vb, bf16x8 pa0, bf16x8 pa1, bf16x8 pa2, bf16x8 pa3) {
;     pv_one<0>(o[0], vb, pa0, pa1, pa2, pa3); pv_one<1>(o[1], vb, pa0, pa1, pa2, pa3); pv_one<2>(o[2], vb, pa0, pa1, pa2, pa3); pv_one<3>(o[3], vb, pa0, pa1, pa2, pa3);
.LBB0_1046:
	s_add_u32 s98, s98, 0x20000
	s_addc_u32 s99, s99, 0
	s_add_u32 s100, s100, 0x20000
	s_addc_u32 s101, s101, 0
	ds_read_b64_tr_b16 v[206:207], v201 offset:0
	ds_read_b64_tr_b16 v[208:209], v201 offset:0x100
	ds_read_b64_tr_b16 v[228:229], v201 offset:0x1000
	ds_read_b64_tr_b16 v[230:231], v201 offset:0x1100
	ds_read_b64_tr_b16 v[232:233], v201 offset:0x2000
	ds_read_b64_tr_b16 v[234:235], v201 offset:0x2100
	ds_read_b64_tr_b16 v[236:237], v201 offset:0x3000
	ds_read_b64_tr_b16 v[238:239], v201 offset:0x3100
	s_waitcnt lgkmcnt(0)
	s_nop 0
	v_mfma_f32_32x32x16_bf16 v[48:63], v[112:115], v[206:209], v[48:63]
	ds_read_b64_tr_b16 v[206:207], v201 offset:0x200
	ds_read_b64_tr_b16 v[208:209], v201 offset:0x300
	v_mfma_f32_32x32x16_bf16 v[48:63], v[116:119], v[228:231], v[48:63]
	ds_read_b64_tr_b16 v[228:229], v201 offset:0x1200
	ds_read_b64_tr_b16 v[230:231], v201 offset:0x1300
	v_mfma_f32_32x32x16_bf16 v[48:63], v[120:123], v[232:235], v[48:63]
	ds_read_b64_tr_b16 v[232:233], v201 offset:0x2200
	ds_read_b64_tr_b16 v[234:235], v201 offset:0x2300
	v_mfma_f32_32x32x16_bf16 v[48:63], v[124:127], v[236:239], v[48:63]
	ds_read_b64_tr_b16 v[236:237], v201 offset:0x3200
	ds_read_b64_tr_b16 v[238:239], v201 offset:0x3300
	s_waitcnt lgkmcnt(0)
	v_mfma_f32_32x32x16_bf16 v[32:47], v[112:115], v[206:209], v[32:47]
	ds_read_b64_tr_b16 v[206:207], v201 offset:0x400
	ds_read_b64_tr_b16 v[208:209], v201 offset:0x500
	v_mfma_f32_32x32x16_bf16 v[32:47], v[116:119], v[228:231], v[32:47]
	ds_read_b64_tr_b16 v[228:229], v201 offset:0x1400
	ds_read_b64_tr_b16 v[230:231], v201 offset:0x1500
	v_mfma_f32_32x32x16_bf16 v[32:47], v[120:123], v[232:235], v[32:47]
	ds_read_b64_tr_b16 v[232:233], v201 offset:0x2400
	ds_read_b64_tr_b16 v[234:235], v201 offset:0x2500
	v_mfma_f32_32x32x16_bf16 v[32:47], v[124:127], v[236:239], v[32:47]
	ds_read_b64_tr_b16 v[236:237], v201 offset:0x3400
	ds_read_b64_tr_b16 v[238:239], v201 offset:0x3500
	s_waitcnt lgkmcnt(0)
	v_mfma_f32_32x32x16_bf16 v[16:31], v[112:115], v[206:209], v[16:31]
	ds_read_b64_tr_b16 v[206:207], v201 offset:0x600
	ds_read_b64_tr_b16 v[208:209], v201 offset:0x700
	v_mfma_f32_32x32x16_bf16 v[16:31], v[116:119], v[228:231], v[16:31]
	ds_read_b64_tr_b16 v[228:229], v201 offset:0x1600
	ds_read_b64_tr_b16 v[230:231], v201 offset:0x1700
	v_mfma_f32_32x32x16_bf16 v[16:31], v[120:123], v[232:235], v[16:31]
	ds_read_b64_tr_b16 v[232:233], v201 offset:0x2600
	ds_read_b64_tr_b16 v[234:235], v201 offset:0x2700
	v_mfma_f32_32x32x16_bf16 v[16:31], v[124:127], v[236:239], v[16:31]
	ds_read_b64_tr_b16 v[236:237], v201 offset:0x3600
	ds_read_b64_tr_b16 v[238:239], v201 offset:0x3700
	s_waitcnt lgkmcnt(0)
	v_mfma_f32_32x32x16_bf16 v[0:15], v[112:115], v[206:209], v[0:15]
	v_max_f32_e32 v112, v128, v129
	v_max3_f32 v112, v112, v130, v131
	v_max3_f32 v112, v112, v132, v133
	v_max3_f32 v112, v112, v134, v135
	v_max3_f32 v112, v112, v136, v137
	v_mfma_f32_32x32x16_bf16 v[0:15], v[116:119], v[228:231], v[0:15]
	v_max3_f32 v112, v112, v138, v139
	v_max3_f32 v112, v112, v140, v141
	v_max3_f32 v112, v112, v142, v143
	v_max3_f32 v112, v112, v96, v97
	v_max3_f32 v112, v112, v98, v99
	v_max3_f32 v112, v112, v100, v101
	v_max3_f32 v112, v112, v102, v103
	v_mfma_f32_32x32x16_bf16 v[0:15], v[120:123], v[232:235], v[0:15]
	v_max3_f32 v112, v112, v104, v105
	v_max3_f32 v112, v112, v106, v107
	v_max3_f32 v112, v112, v108, v109
	v_max3_f32 v113, v112, v110, v111
	v_mfma_f32_32x32x16_bf16 v[0:15], v[124:127], v[236:239], v[0:15]
	v_cmp_ngt_f32_e32 vcc, s83, v200
	v_cmp_ge_f32_e64 s[8:9], s63, v113
	s_and_b64 s[8:9], vcc, s[8:9]
	s_cmp_eq_u64 s[8:9], exec
	v_mov_b32_e32 v112, 1.0
	s_cbranch_scc0 .LBB0_1058

; DI void partialSM(f32x16& p0, f32x16& p1, float& m_reg, f32x16& negm, float& alpha) {
;     ...
;     { auto rr = __builtin_amdgcn_permlane32_swap(__float_as_uint(pmax), __float_as_uint(pmax), false, false);
;       pmax = fmaxf(__uint_as_float(rr[0]), __uint_as_float(rr[1])); }
;     const bool first = m_reg < -1e29f;
;     if (__builtin_expect(__all(!first && pmax <= THR2), 1)) { alpha = 1.f; }
;     else {
;         const float d = first ? pmax : fmaxf(pmax, 0.f);
;         alpha = first ? 0.f : __builtin_amdgcn_exp2f(-d);
;         m_reg = first ? pmax : m_reg + d;
; #pragma unroll
;         for (int r = 0; r < 16; ++r) { p0[r] -= d; p1[r] -= d; negm[r] = -m_reg; }
;     }
.LBB0_1057:
	v_mov_b32_e32 v81, v80
	s_nop 1
	v_permlane32_swap_b32_e32 v80, v81
	v_max_f32_e32 v80, v80, v81
	v_max_f32_e32 v64, v80, v80
	v_max_f32_e32 v65, 0, v64
	v_cndmask_b32_e32 v64, v80, v65, vcc
	v_exp_f32_e64 v66, -v64
	v_add_f32_e32 v65, v200, v65
	v_cndmask_b32_e32 v200, v80, v65, vcc
	v_xor_b32_e32 v80, 0x80000000, v200
	v_cndmask_b32_e32 v224, 0, v66, vcc
	v_pk_add_f32 v[128:129], v[128:129], v[64:65] op_sel_hi:[1,0] neg_lo:[0,1] neg_hi:[0,1]
	v_pk_add_f32 v[130:131], v[130:131], v[64:65] op_sel_hi:[1,0] neg_lo:[0,1] neg_hi:[0,1]
	v_pk_add_f32 v[132:133], v[132:133], v[64:65] op_sel_hi:[1,0] neg_lo:[0,1] neg_hi:[0,1]
	v_pk_add_f32 v[134:135], v[134:135], v[64:65] op_sel_hi:[1,0] neg_lo:[0,1] neg_hi:[0,1]
	v_pk_add_f32 v[136:137], v[136:137], v[64:65] op_sel_hi:[1,0] neg_lo:[0,1] neg_hi:[0,1]
	v_pk_add_f32 v[138:139], v[138:139], v[64:65] op_sel_hi:[1,0] neg_lo:[0,1] neg_hi:[0,1]
	v_pk_add_f32 v[140:141], v[140:141], v[64:65] op_sel_hi:[1,0] neg_lo:[0,1] neg_hi:[0,1]
	v_pk_add_f32 v[142:143], v[142:143], v[64:65] op_sel_hi:[1,0] neg_lo:[0,1] neg_hi:[0,1]
	v_sub_f32_e32 v127, v127, v64
	v_sub_f32_e32 v126, v126, v64
	v_sub_f32_e32 v125, v125, v64
	v_sub_f32_e32 v124, v124, v64
	v_sub_f32_e32 v123, v123, v64
	v_sub_f32_e32 v122, v122, v64
	v_sub_f32_e32 v121, v121, v64
	v_sub_f32_e32 v120, v120, v64
	v_sub_f32_e32 v119, v119, v64
	v_sub_f32_e32 v118, v118, v64
	v_sub_f32_e32 v117, v117, v64
	v_sub_f32_e32 v116, v116, v64
	v_sub_f32_e32 v115, v115, v64
	v_sub_f32_e32 v114, v114, v64
	v_sub_f32_e32 v113, v113, v64
	v_sub_f32_e32 v112, v112, v64
	v_mov_b32_e32 v81, v80
	v_mov_b32_e32 v82, v80
	v_mov_b32_e32 v83, v80
	v_mov_b32_e32 v84, v80
	v_mov_b32_e32 v85, v80
	v_mov_b32_e32 v86, v80
	v_mov_b32_e32 v87, v80
	v_mov_b32_e32 v88, v80
	v_mov_b32_e32 v89, v80
	v_mov_b32_e32 v90, v80
	v_mov_b32_e32 v91, v80
	v_mov_b32_e32 v92, v80
	v_mov_b32_e32 v93, v80
	v_mov_b32_e32 v94, v80
	v_mov_b32_e32 v95, v80
	v_mov_b32_e32 v64, v80
	v_mov_b32_e32 v65, v80
	v_mov_b32_e32 v66, v80
	v_mov_b32_e32 v67, v80
	v_mov_b32_e32 v68, v80
	v_mov_b32_e32 v69, v80
	v_mov_b32_e32 v70, v80
	v_mov_b32_e32 v71, v80
	v_mov_b32_e32 v72, v80
	v_mov_b32_e32 v73, v80
	v_mov_b32_e32 v74, v80
	v_mov_b32_e32 v75, v80
	v_mov_b32_e32 v76, v80
	v_mov_b32_e32 v77, v80
	v_mov_b32_e32 v78, v80
	v_mov_b32_e32 v79, v80
	s_branch .LBB0_1040
.LBB0_1058:
	v_mov_b32_e32 v64, v113
	s_nop 1
	v_permlane32_swap_b32_e32 v113, v64
	v_max_f32_e32 v113, v113, v64
	v_max_f32_e32 v64, v113, v113
	v_max_f32_e32 v65, 0, v64
	v_cndmask_b32_e32 v64, v113, v65, vcc
	v_exp_f32_e64 v66, -v64
	v_add_f32_e32 v65, v200, v65
	v_cndmask_b32_e32 v200, v113, v65, vcc
	v_xor_b32_e32 v80, 0x80000000, v200
	v_cndmask_b32_e32 v112, 0, v66, vcc
	v_pk_add_f32 v[128:129], v[128:129], v[64:65] op_sel_hi:[1,0] neg_lo:[0,1] neg_hi:[0,1]
	v_pk_add_f32 v[130:131], v[130:131], v[64:65] op_sel_hi:[1,0] neg_lo:[0,1] neg_hi:[0,1]
	v_pk_add_f32 v[132:133], v[132:133], v[64:65] op_sel_hi:[1,0] neg_lo:[0,1] neg_hi:[0,1]
	v_pk_add_f32 v[134:135], v[134:135], v[64:65] op_sel_hi:[1,0] neg_lo:[0,1] neg_hi:[0,1]
	v_pk_add_f32 v[136:137], v[136:137], v[64:65] op_sel_hi:[1,0] neg_lo:[0,1] neg_hi:[0,1]
	v_pk_add_f32 v[138:139], v[138:139], v[64:65] op_sel_hi:[1,0] neg_lo:[0,1] neg_hi:[0,1]
	v_pk_add_f32 v[140:141], v[140:141], v[64:65] op_sel_hi:[1,0] neg_lo:[0,1] neg_hi:[0,1]
	v_pk_add_f32 v[142:143], v[142:143], v[64:65] op_sel_hi:[1,0] neg_lo:[0,1] neg_hi:[0,1]
	v_sub_f32_e32 v111, v111, v64
	v_sub_f32_e32 v110, v110, v64
	v_sub_f32_e32 v109, v109, v64
	v_sub_f32_e32 v108, v108, v64
	v_sub_f32_e32 v107, v107, v64
	v_sub_f32_e32 v106, v106, v64
	v_sub_f32_e32 v105, v105, v64
	v_sub_f32_e32 v104, v104, v64
	v_sub_f32_e32 v103, v103, v64
	v_sub_f32_e32 v102, v102, v64
	v_sub_f32_e32 v101, v101, v64
	v_sub_f32_e32 v100, v100, v64
	v_sub_f32_e32 v99, v99, v64
	v_sub_f32_e32 v98, v98, v64
	v_sub_f32_e32 v97, v97, v64
	v_sub_f32_e32 v96, v96, v64
	v_mov_b32_e32 v81, v80
	v_mov_b32_e32 v82, v80
	v_mov_b32_e32 v83, v80
	v_mov_b32_e32 v84, v80
	v_mov_b32_e32 v85, v80
	v_mov_b32_e32 v86, v80
	v_mov_b32_e32 v87, v80
	v_mov_b32_e32 v88, v80
	v_mov_b32_e32 v89, v80
	v_mov_b32_e32 v90, v80
	v_mov_b32_e32 v91, v80
	v_mov_b32_e32 v92, v80
	v_mov_b32_e32 v93, v80
	v_mov_b32_e32 v94, v80
	v_mov_b32_e32 v95, v80
	v_mov_b32_e32 v64, v80
	v_mov_b32_e32 v65, v80
	v_mov_b32_e32 v66, v80
	v_mov_b32_e32 v67, v80
	v_mov_b32_e32 v68, v80
	v_mov_b32_e32 v69, v80
	v_mov_b32_e32 v70, v80
	v_mov_b32_e32 v71, v80
	v_mov_b32_e32 v72, v80
	v_mov_b32_e32 v73, v80
	v_mov_b32_e32 v74, v80
	v_mov_b32_e32 v75, v80
	v_mov_b32_e32 v76, v80
	v_mov_b32_e32 v77, v80
	v_mov_b32_e32 v78, v80
	v_mov_b32_e32 v79, v80
	s_branch .LBB0_1047
